# attention: one static s_setprio 1 at section entry for the younger wave half (waves 4-7), reset at the section exit
# speedup vs baseline: 1.0119x; 1.0013x over previous
.LBB0_246:
	v_readlane_b32 s0, v255, 17
	s_cmpk_gt_i32 s0, 0x7ff
	s_movk_i32 s28, 0x101
	s_cbranch_scc1 .LBB0_262
	s_mov_b32 s32, 0
	v_readlane_b32 s98, v255, 18
	s_nop 1
	s_cmp_gt_u32 s98, 3
	s_cbranch_scc0 .Lprio_skip
	s_setprio 1
.Lprio_skip:
	s_waitcnt vmcnt(4)
	v_and_b32_e32 v1, 64, v185
	v_xor_b32_e32 v0, 16, v185
	v_add_u32_e32 v1, 64, v1
	v_cmp_lt_i32_e32 vcc, v0, v1
	s_add_u32 s4, s70, 0x9100000
	v_readlane_b32 s0, v255, 18
	v_cndmask_b32_e32 v0, v185, v0, vcc
	v_lshlrev_b32_e32 v159, 2, v0
	v_xor_b32_e32 v0, 32, v185
	s_addc_u32 s5, s71, 0
	s_lshl_b32 s2, s0, 4
	v_cmp_lt_i32_e32 vcc, v0, v1
	s_add_u32 s6, s70, 0x39900000
	v_readlane_b32 s12, v255, 17
	v_cndmask_b32_e32 v0, v185, v0, vcc
	v_lshlrev_b32_e32 v160, 2, v0
	s_addc_u32 s7, s71, 0
	s_sub_i32 s3, 64, s2
	s_lshl_b32 s10, s12, 7
	s_waitcnt lgkmcnt(0)
	s_lshl_b32 s11, s42, 7
	s_branch .LBB0_249

.LBB0_262:
	s_setprio 0
	s_waitcnt vmcnt(0)
	v_readlane_b32 s0, v255, 17
	s_cmpk_gt_i32 s0, 0x3ff
	s_cbranch_scc1 .LBB0_269
	s_add_u32 s4, s70, 0x31500000
	s_addc_u32 s5, s71, 0
	s_add_u32 s52, s70, 0x41900000
	s_addc_u32 s53, s71, 0
	s_add_u32 s54, s70, 0x9100000
	v_readlane_b32 s2, v255, 21
	s_addc_u32 s55, s71, 0
	v_readlane_b32 s3, v255, 22
	s_lshl_b32 s0, s2, 3
	s_lshl_b32 s2, s2, 11
	s_ashr_i32 s3, s2, 31
	v_readlane_b32 s8, v252, 9
	s_lshl_b64 s[2:3], s[2:3], 2
	v_readlane_b32 s14, v252, 15
	v_readlane_b32 s15, v252, 16
	s_add_u32 s56, s14, s2
	v_readlane_b32 s16, v252, 17
	s_addc_u32 s57, s15, s3
	v_readlane_b32 s17, v252, 18
	s_add_u32 s58, s16, s2
	v_readlane_b32 s2, v255, 19
	v_readlane_b32 s6, v255, 18
	v_readlane_b32 s10, v252, 11
	s_addc_u32 s59, s17, s3
	s_ashr_i32 s2, s2, 8
	s_lshl_b32 s3, s6, 5
	v_readlane_b32 s12, v252, 13
	s_and_b32 s10, s3, 0x60
	s_lshl_b32 s3, s2, 15
	v_readlane_b32 s11, v252, 12
	v_readlane_b32 s13, v252, 14
	v_readlane_b32 s18, v252, 19
	v_readlane_b32 s19, v252, 20
	v_readlane_b32 s20, v252, 21
	v_readlane_b32 s21, v252, 22
	v_readlane_b32 s22, v252, 23
	v_readlane_b32 s23, v252, 24
	s_add_i32 s12, s3, 0
	s_mul_i32 s3, s6, 0x4200
	v_readlane_b32 s24, v255, 17
	s_add_i32 s11, s12, 0x8800
	s_add_i32 s12, s12, 0xc800
	s_add_i32 s13, s3, 0
	s_lshl_b32 s14, s2, 7
	s_or_b32 s15, s10, 4
	s_or_b32 s16, s10, 8
	s_or_b32 s17, s10, 12
	s_or_b32 s18, s10, 16
	s_or_b32 s19, s10, 20
	s_or_b32 s20, s10, 24
	s_or_b32 s21, s10, 28
	s_lshl_b32 s22, s24, 4
	s_waitcnt lgkmcnt(0)
	s_lshl_b32 s23, s42, 4
	v_readlane_b32 s9, v252, 10
	s_branch .LBB0_265
